# P0 closing cooperative-groups grid sync replaced by the XCD two-level barrier; barrier words zeroed at kernel start behind a ready flag
# speedup vs baseline: 1.0686x; 1.0126x over previous
; #define LAS __attribute__((address_space(3)))
; __device__ __forceinline__ CArgsP get_args() { CArgsP p = (CArgsP)__builtin_amdgcn_kernarg_segment_ptr(); asm volatile("" : "+s"(p)); return p; }
; __device__ __forceinline__ void convert_weights(CArgsP a, LAS unsigned char* lds, int wave, int lane, int which, int gb, int NGB) {
;     unsigned char* ws = a->ws;
;     constexpr int I0 = 22 * 16, I1 = 4 * 44, I2 = 14 * 16, I3 = 4 * 16;
;     const int NIT = which == 0 ? I0 + I1 + I2 : I0 + I1 + I3;
;     for (int it = gb; it < NIT; it += NGB) {
;         int r = it;
;         if (r < I0) { const int pn = r >> 4, kb = r & 15;
;             convert_tile(which == 0 ? a->in[8] : a->in[28], 1024, 5632, which == 0 ? a->in[7] : a->in[27], (bf16_t*)(ws + (which == 0 ? WS_W1I : WS_W2I)), pn, 64 * kb, 0, lds, wave, lane); continue; }
; __global__ void __launch_bounds__(512, 2) mega_fwd(Args a_unused) {
;     ...
;     const int tid = threadIdx.x, lane = tid & 63, wave = __builtin_amdgcn_readfirstlane(tid >> 6);
;     const int G = gridDim.x, bx = blockIdx.x;
;     if (tid < 64) ((LAS unsigned*)(lds + 131072))[tid] = 0u;
;     __syncthreads();
;     { CArgsP a = get_args(); phase0(a, lds, wave, lane);
;       if (bx == 0) { unsigned* bw = (unsigned*)(a->ws + WS_BAR); for (int i = tid; i < (int)(BAR_BYTES / 4); i += 512) bw[i] = 0u; } }
_Z8mega_fwd4Args:
	s_load_dwordx2 s[60:61], s[0:1], 0x100
	s_load_dword s78, s[0:1], 0x108
	s_mov_b64 s[92:93], s[0:1]
	v_and_b32_e32 v164, 0x3ff, v0
	s_add_u32 s10, s92, 0x100
	v_cmp_lt_u32_e64 s[0:1], 63, v164
	s_addc_u32 s11, s93, 0
	v_readfirstlane_b32 s44, v164
	v_writelane_b32 v250, s0, 0
	v_cmp_gt_u32_e64 s[8:9], 64, v164
	v_lshl_add_u32 v149, v164, 2, 0
	v_writelane_b32 v250, s1, 1
	s_and_saveexec_b64 s[4:5], s[8:9]
	v_lshl_add_u32 v1, v164, 2, 0
	v_add_u32_e32 v1, 0x20000, v1
	v_mov_b32_e32 v2, 0
	ds_write_b32 v1, v2
	s_or_b64 exec, exec, s[4:5]
	s_mov_b64 s[18:19], s[92:93]
	s_waitcnt lgkmcnt(0)
	s_barrier
	s_cmp_lg_u32 s2, 0
	s_cbranch_scc1 .Lz_done
	s_load_dwordx2 s[16:17], s[92:93], 0xf8
	v_lshlrev_b32_e32 v1, 2, v164
	v_mov_b32_e32 v2, 0
	s_waitcnt lgkmcnt(0)
	s_add_u32 s16, s16, 0x80000
	s_addc_u32 s17, s17, 0
	global_store_dword v1, v2, s[16:17]
	global_store_dword v1, v2, s[16:17] offset:2048
	v_add_u32_e32 v1, 0x1000, v1
	global_store_dword v1, v2, s[16:17]
	global_store_dword v1, v2, s[16:17] offset:2048
	v_add_u32_e32 v1, 0x1000, v1
	global_store_dword v1, v2, s[16:17]
	global_store_dword v1, v2, s[16:17] offset:2048
	v_add_u32_e32 v1, 0x1000, v1
	global_store_dword v1, v2, s[16:17]
	global_store_dword v1, v2, s[16:17] offset:2048
	s_waitcnt vmcnt(0)
	s_barrier
	s_cmp_lg_u32 s44, 0
	s_cbranch_scc1 .Lz_done
	buffer_wbl2 sc1
	s_waitcnt vmcnt(0)
	v_mov_b32_e32 v1, 0x3e80
	v_mov_b32_e32 v2, 0x5a17c0de
	global_store_dword v1, v2, s[16:17] sc0 sc1
	s_waitcnt vmcnt(0)
	buffer_inv sc1
	s_waitcnt vmcnt(0)
.Lz_done:
	s_load_dwordx2 s[16:17], s[18:19], 0xf8
	v_and_b32_e32 v148, 63, v164
	s_lshr_b32 s79, s44, 6
	s_cmpk_gt_i32 s2, 0x2ef
	v_lshlrev_b32_e32 v165, 2, v148
	v_lshlrev_b32_e32 v150, 3, v164
	s_cbranch_scc1 .LBB0_39
	s_lshl_b32 s0, s79, 3
	s_and_b32 s3, s44, 0xc0
	s_and_b32 s12, s0, 0x1fffffe0
	s_or_b32 s6, s0, 24
	s_waitcnt lgkmcnt(0)
	s_add_u32 s22, s16, 0x1400000
	s_addc_u32 s23, s17, 0
	s_or_b32 s7, s0, 1
	s_add_u32 s24, s16, 0xe00000
	s_movk_i32 s4, 0xc0
	v_and_b32_e32 v5, 32, v164
	s_addc_u32 s25, s17, 0
	v_lshlrev_b32_e32 v3, 2, v148
	v_and_or_b32 v45, v150, s4, v5
	s_add_u32 s26, s16, 0x300000
	v_lshrrev_b32_e32 v5, 5, v148
	v_and_b32_e32 v4, 28, v3
	v_or_b32_e32 v43, s3, v148
	s_addc_u32 s27, s17, 0
	v_mul_u32_u24_e32 v5, 0xb00, v5
	s_movk_i32 s4, 0x60
	s_lshl_b32 s13, s2, 4
	v_and_b32_e32 v1, 0xe0, v3
	s_mov_b32 s21, 0
	v_mov_b32_e32 v2, 0
	v_lshl_add_u32 v42, v148, 4, 0
	s_mul_i32 s1, s79, 0x2080
	v_lshl_add_u32 v44, v43, 2, 0
	s_mul_i32 s3, s12, 0x410
	s_mulk_i32 s6, 0x410
	s_mulk_i32 s7, 0x410
	v_and_or_b32 v46, v3, s4, v5
	v_cmp_gt_u32_e64 s[4:5], 8, v4
	s_add_i32 s30, s13, 0xffffdf00
	s_lshl_b32 s31, s60, 4
	s_lshl_b32 s33, s2, 6
	s_lshl_b32 s34, s60, 6
	s_movk_i32 s35, 0xd00
	s_movk_i32 s36, 0x7fff
	s_mov_b32 s37, 0xffff0000
	s_lshl_b32 s20, s12, 1
	v_lshlrev_b32_e32 v38, 2, v4
	v_mov_b32_e32 v47, 0x3420
	v_mov_b32_e32 v48, 0x5800
	s_mov_b32 s38, s2
	s_branch .LBB0_6

; #define LAS __attribute__((address_space(3)))
; __device__ __forceinline__ CArgsP get_args() { CArgsP p = (CArgsP)__builtin_amdgcn_kernarg_segment_ptr(); asm volatile("" : "+s"(p)); return p; }
; __device__ __forceinline__ unsigned xb_ld(unsigned* p)              { return __hip_atomic_load(p, __ATOMIC_RELAXED, __HIP_MEMORY_SCOPE_AGENT); }
; __device__ __forceinline__ unsigned xb_add(unsigned* p, unsigned v) { return __hip_atomic_fetch_add(p, v, __ATOMIC_RELAXED, __HIP_MEMORY_SCOPE_AGENT); }
; __device__ __forceinline__ unsigned xb_xcc_id() { return (unsigned)__builtin_amdgcn_s_getreg((3 << 11) | 20) & 0xFu; }
; __device__ __forceinline__ XcdBarrier xcd_barrier_post(unsigned* bar, volatile LAS unsigned* st) {
;     XcdBarrier b; b.bar = bar; b.x = xb_xcc_id(); b.st = st;
;     if (threadIdx.x == 0) (void)xb_add(&bar[XB_XCNT(b.x)], 1u);
;     return b;
; }
; __device__ __forceinline__ void xcd_barrier_complete(unsigned* bar, unsigned x, unsigned& nloc, unsigned& nx) {
;     const unsigned G = gridDim.x * gridDim.y * gridDim.z;
;     unsigned sum, cnt, mine, sp = 0u;
;     for (;;) {
;         sum = 0u; cnt = 0u; mine = 0u;
; #pragma unroll
;         for (unsigned j = 0; j < 16; ++j) { const unsigned c = xb_ld(&bar[XB_XCNT(j)]); sum += c; cnt += (c > 0u) ? 1u : 0u; mine = (j == x) ? c : mine; }
;         if (sum == G) break;
;         __builtin_amdgcn_s_sleep(1);
;         if ((++sp & 255u) == 0u) { if (xb_ld(&bar[XB_TMO])) break; if (sp > XB_SPIN_CAP) { atomicAdd(&bar[XB_TMO], 1u); break; } }
;     }
;     nloc = mine > 0u ? mine : 1u; nx = cnt > 0u ? cnt : 1u;
; }
; __device__ __forceinline__ void xcd_barrier(const XcdBarrier& b) {
;     asm volatile("s_waitcnt vmcnt(0)" ::: "memory");
;     __syncthreads();
;     if (threadIdx.x == 0) {
;         unsigned* bar = b.bar;
;         __builtin_amdgcn_s_waitcnt(0);
;         unsigned nloc = b.st[0], nx = b.st[1];
;         if (nloc == 0u) { xcd_barrier_complete(bar, b.x, nloc, nx); b.st[0] = nloc; b.st[1] = nx; }
; __global__ void __launch_bounds__(512, 2) mega_fwd(Args a_unused) {
;     ...
;       if (bx == 0) { unsigned* bw = (unsigned*)(a->ws + WS_BAR); for (int i = tid; i < (int)(BAR_BYTES / 4); i += 512) bw[i] = 0u; } }
;     grid.sync();
;     { CArgsP a = get_args(); (void)xcd_barrier_post((unsigned*)(a->ws + WS_BAR), (volatile LAS unsigned*)(lds + LDS_MISC)); }
.LBB0_75:
	s_waitcnt lgkmcnt(0)
	v_writelane_b32 v250, s44, 3
	v_cmp_eq_u32_e64 s[52:53], 0, v164
	v_writelane_b32 v251, s16, 0
	v_writelane_b32 v251, s17, 1
	v_writelane_b32 v251, s18, 2
	v_writelane_b32 v251, s19, 3
	v_writelane_b32 v251, s20, 4
	v_writelane_b32 v251, s21, 5
	v_writelane_b32 v251, s22, 6
	v_writelane_b32 v251, s23, 7
	v_writelane_b32 v251, s24, 8
	v_writelane_b32 v251, s25, 9
	v_writelane_b32 v251, s26, 10
	v_writelane_b32 v251, s27, 11
	v_writelane_b32 v251, s38, 12
	v_writelane_b32 v251, s39, 13
	v_writelane_b32 v251, s40, 14
	v_writelane_b32 v251, s41, 15
	v_writelane_b32 v251, s42, 16
	v_writelane_b32 v251, s43, 17
	v_writelane_b32 v251, s44, 18
	v_writelane_b32 v251, s45, 19
	v_writelane_b32 v251, s46, 20
	v_writelane_b32 v251, s47, 21
	v_writelane_b32 v251, s48, 22
	v_writelane_b32 v251, s49, 23
	v_writelane_b32 v251, s50, 24
	v_writelane_b32 v251, s51, 25
	v_writelane_b32 v251, s54, 26
	v_writelane_b32 v251, s55, 27
	v_writelane_b32 v251, s56, 28
	v_writelane_b32 v251, s57, 29
	v_writelane_b32 v251, s58, 30
	v_writelane_b32 v251, s59, 31
	v_writelane_b32 v251, s66, 32
	v_writelane_b32 v251, s67, 33
	v_writelane_b32 v251, s68, 34
	v_writelane_b32 v251, s69, 35
	v_readlane_b32 s94, v0, 0
	v_readlane_b32 s95, v1, 0
	v_readlane_b32 s96, v2, 0
	v_readlane_b32 s97, v3, 0
	s_nop 1
	v_writelane_b32 v252, s94, 0
	v_writelane_b32 v252, s95, 1
	v_writelane_b32 v252, s96, 2
	v_writelane_b32 v252, s97, 3
	v_readlane_b32 s94, v4, 0
	v_readlane_b32 s95, v5, 0
	v_readlane_b32 s96, v6, 0
	v_readlane_b32 s97, v7, 0
	s_nop 1
	v_writelane_b32 v252, s94, 4
	v_writelane_b32 v252, s95, 5
	v_writelane_b32 v252, s96, 6
	v_writelane_b32 v252, s97, 7
	v_readlane_b32 s94, v8, 0
	v_readlane_b32 s95, v9, 0
	v_readlane_b32 s96, v10, 0
	v_readlane_b32 s97, v11, 0
	s_nop 1
	v_writelane_b32 v252, s94, 8
	v_writelane_b32 v252, s95, 9
	v_writelane_b32 v252, s96, 10
	v_writelane_b32 v252, s97, 11
	v_readlane_b32 s94, v12, 0
	v_readlane_b32 s95, v13, 0
	v_readlane_b32 s96, v14, 0
	v_readlane_b32 s97, v15, 0
	s_nop 1
	v_writelane_b32 v252, s94, 12
	v_writelane_b32 v252, s95, 13
	v_writelane_b32 v252, s96, 14
	v_writelane_b32 v252, s97, 15
	v_readlane_b32 s94, v16, 0
	v_readlane_b32 s95, v17, 0
	s_nop 1
	v_writelane_b32 v252, s94, 16
	v_writelane_b32 v252, s95, 17
	s_getreg_b32 s0, hwreg(HW_REG_XCC_ID, 0, 4)
	s_and_saveexec_b64 s[4:5], s[52:53]
	s_cbranch_execz .Lcg_post_done
	s_load_dwordx2 s[6:7], s[92:93], 0xf8
	v_mov_b32_e32 v0, 0x83e80
	s_mov_b32 s1, 0
	s_waitcnt lgkmcnt(0)
.Lcg_flag:
	global_load_dword v1, v0, s[6:7] sc1
	s_waitcnt vmcnt(0)
	v_readfirstlane_b32 s3, v1
	s_cmp_eq_u32 s3, 0x5a17c0de
	s_cbranch_scc1 .Lcg_flag_ok
	s_sleep 1
	s_add_u32 s1, s1, 1
	s_cmp_lt_u32 s1, 0x100000
	s_cbranch_scc1 .Lcg_flag
.Lcg_flag_ok:
	s_lshl_b32 s0, s0, 8
	s_and_b32 s0, s0, 0xf00
	v_mov_b32_e32 v0, 0x80000
	v_mov_b32_e32 v1, 1
	s_add_u32 s0, s6, s0
	s_addc_u32 s1, s7, 0
	global_atomic_add v0, v1, s[0:1] offset:1024
.Lcg_post_done:
	s_or_b64 exec, exec, s[4:5]
	s_mov_b64 s[10:11], s[92:93]
	s_getreg_b32 s0, hwreg(HW_REG_XCC_ID, 0, 4)
	s_waitcnt vmcnt(0)
	s_waitcnt lgkmcnt(0)
	s_barrier
	s_and_saveexec_b64 s[4:5], s[52:53]
	s_cbranch_execz .Lcg_277
	s_add_i32 s1, 0, 0x20040
	v_mov_b32_e32 v0, s1
	s_load_dwordx2 s[10:11], s[10:11], 0xf8
	s_waitcnt vmcnt(0) expcnt(0) lgkmcnt(0)
	ds_read_b32 v2, v0
	s_add_i32 s1, 0, 0x20044
	v_mov_b32_e32 v0, s1
	ds_read_b32 v0, v0
	s_and_b32 s0, s0, 15
	s_waitcnt lgkmcnt(1)
	v_cmp_ne_u32_e32 vcc, 0, v2
	s_cbranch_vccnz .Lcg_241
	s_add_u32 s12, s10, 0x80200
	s_addc_u32 s13, s11, 0
	s_add_u32 s14, s10, 0x80400
	s_addc_u32 s15, s11, 0
	s_add_u32 s16, s10, 0x80500
	s_addc_u32 s17, s11, 0
	s_add_u32 s18, s10, 0x80600
	s_addc_u32 s19, s11, 0
	s_add_u32 s20, s10, 0x80700
	s_addc_u32 s21, s11, 0
	s_add_u32 s22, s10, 0x80800
	s_addc_u32 s23, s11, 0
	s_add_u32 s24, s10, 0x80900
	s_addc_u32 s25, s11, 0
	s_add_u32 s26, s10, 0x80a00
	s_addc_u32 s27, s11, 0
	s_add_u32 s38, s10, 0x80b00
	s_addc_u32 s39, s11, 0
	s_add_u32 s40, s10, 0x80c00
	s_addc_u32 s41, s11, 0
	s_add_u32 s42, s10, 0x80d00
	s_addc_u32 s43, s11, 0
	s_add_u32 s44, s10, 0x80e00
	s_addc_u32 s45, s11, 0
	s_add_u32 s46, s10, 0x80f00
	s_addc_u32 s47, s11, 0
	s_add_u32 s48, s10, 0x81000
	s_addc_u32 s49, s11, 0
	s_add_u32 s50, s10, 0x81100
	s_addc_u32 s51, s11, 0
	s_add_u32 s54, s10, 0x81200
	s_addc_u32 s55, s11, 0
	s_mul_i32 s1, s61, s78
	s_add_u32 s56, s10, 0x81300
	s_mul_i32 s1, s1, s60
	s_addc_u32 s57, s11, 0
	s_mov_b32 s3, 1
	v_mov_b32_e32 v16, 0
	s_branch .Lcg_229

; #define LAS __attribute__((address_space(3)))
; __device__ __forceinline__ CArgsP get_args() { CArgsP p = (CArgsP)__builtin_amdgcn_kernarg_segment_ptr(); asm volatile("" : "+s"(p)); return p; }
; __device__ __forceinline__ unsigned xb_xcc_id() { return (unsigned)__builtin_amdgcn_s_getreg((3 << 11) | 20) & 0xFu; }
;     __device__ bool next(int i, pg8::Unit& u) const { if (i) return false; u.pm = pm; u.pn = pn; return true; }
; __device__ __forceinline__ void xcd_barrier(const XcdBarrier& b) {
;     ...
;     }
;     __syncthreads();
; }
; __device__ __forceinline__ void grid_bar(LAS unsigned char* lds) {
;     CArgsP a = get_args(); XcdBarrier b; b.bar = (unsigned*)(a->ws + WS_BAR); b.x = xb_xcc_id(); b.st = (volatile LAS unsigned*)(lds + LDS_MISC);
;     xcd_barrier(b);
;     __device__ bool next(int i, pg8::Unit& u) const {
;         long L = (long)i * G + c;
;         if (G == 256 && nN == 22) {
;             if (c >= G - 4) { if (i >= 3) return false; }
;             else if (c >= G - 12 && i == 5) { const int k = c - (G - 12); L = (long)(3 + (k >> 2)) * G + (G - 4 + (k & 3)); }
;         }
;         if (L < nS) { u.pm = nM; u.pn = (int)L; return true; }
;         L -= nS; if (L >= nwg) return false;
;         int wgid = (int)L; { const int q = nwg / pg8::NXCD, r = nwg % pg8::NXCD, xcd = wgid % pg8::NXCD, off = wgid / pg8::NXCD; wgid = (xcd < r ? xcd * (q + 1) : r * (q + 1) + (xcd - r) * q) + off; }
;         const int nig = pg8::WGM * nN, gid = wgid / nig, fm = gid * pg8::WGM, gsz = (nM - fm) < pg8::WGM ? (nM - fm) : pg8::WGM;
;         u.pm = fm + ((wgid % nig) % gsz); u.pn = (wgid % nig) / gsz; return true;
.Lcg_277:
	s_or_b64 exec, exec, s[4:5]
	s_cmp_lg_u32 s2, 0
	s_cbranch_scc1 .Lcg_noreset
	s_cmp_lg_u32 s44, 0
	s_cbranch_scc1 .Lcg_noreset
	s_load_dwordx2 s[6:7], s[92:93], 0xf8
	v_mov_b32_e32 v0, 0x83e80
	v_mov_b32_e32 v1, 0
	s_waitcnt lgkmcnt(0)
	global_store_dword v0, v1, s[6:7] sc0 sc1
.Lcg_noreset:
	v_readlane_b32 s94, v252, 0
	v_readlane_b32 s95, v252, 1
	v_readlane_b32 s96, v252, 2
	v_readlane_b32 s97, v252, 3
	s_nop 1
	v_writelane_b32 v0, s94, 0
	v_writelane_b32 v1, s95, 0
	v_writelane_b32 v2, s96, 0
	v_writelane_b32 v3, s97, 0
	v_readlane_b32 s94, v252, 4
	v_readlane_b32 s95, v252, 5
	v_readlane_b32 s96, v252, 6
	v_readlane_b32 s97, v252, 7
	s_nop 1
	v_writelane_b32 v4, s94, 0
	v_writelane_b32 v5, s95, 0
	v_writelane_b32 v6, s96, 0
	v_writelane_b32 v7, s97, 0
	v_readlane_b32 s94, v252, 8
	v_readlane_b32 s95, v252, 9
	v_readlane_b32 s96, v252, 10
	v_readlane_b32 s97, v252, 11
	s_nop 1
	v_writelane_b32 v8, s94, 0
	v_writelane_b32 v9, s95, 0
	v_writelane_b32 v10, s96, 0
	v_writelane_b32 v11, s97, 0
	v_readlane_b32 s94, v252, 12
	v_readlane_b32 s95, v252, 13
	v_readlane_b32 s96, v252, 14
	v_readlane_b32 s97, v252, 15
	s_nop 1
	v_writelane_b32 v12, s94, 0
	v_writelane_b32 v13, s95, 0
	v_writelane_b32 v14, s96, 0
	v_writelane_b32 v15, s97, 0
	v_readlane_b32 s94, v252, 16
	v_readlane_b32 s95, v252, 17
	s_nop 1
	v_writelane_b32 v16, s94, 0
	v_writelane_b32 v17, s95, 0
	v_readlane_b32 s16, v251, 0
	v_readlane_b32 s17, v251, 1
	v_readlane_b32 s18, v251, 2
	v_readlane_b32 s19, v251, 3
	v_readlane_b32 s20, v251, 4
	v_readlane_b32 s21, v251, 5
	v_readlane_b32 s22, v251, 6
	v_readlane_b32 s23, v251, 7
	v_readlane_b32 s24, v251, 8
	v_readlane_b32 s25, v251, 9
	v_readlane_b32 s26, v251, 10
	v_readlane_b32 s27, v251, 11
	v_readlane_b32 s38, v251, 12
	v_readlane_b32 s39, v251, 13
	v_readlane_b32 s40, v251, 14
	v_readlane_b32 s41, v251, 15
	v_readlane_b32 s42, v251, 16
	v_readlane_b32 s43, v251, 17
	v_readlane_b32 s44, v251, 18
	v_readlane_b32 s45, v251, 19
	v_readlane_b32 s46, v251, 20
	v_readlane_b32 s47, v251, 21
	v_readlane_b32 s48, v251, 22
	v_readlane_b32 s49, v251, 23
	v_readlane_b32 s50, v251, 24
	v_readlane_b32 s51, v251, 25
	v_readlane_b32 s54, v251, 26
	v_readlane_b32 s55, v251, 27
	v_readlane_b32 s56, v251, 28
	v_readlane_b32 s57, v251, 29
	v_readlane_b32 s58, v251, 30
	v_readlane_b32 s59, v251, 31
	v_readlane_b32 s66, v251, 32
	v_readlane_b32 s67, v251, 33
	v_readlane_b32 s68, v251, 34
	v_readlane_b32 s69, v251, 35
	s_mov_b64 s[10:11], s[92:93]
	s_waitcnt lgkmcnt(0)
	s_barrier
	s_mov_b64 s[20:21], s[92:93]
	s_load_dwordx2 s[18:19], s[20:21], 0xf8
	v_mov_b32_e32 v8, v164
	s_waitcnt lgkmcnt(0)
	s_add_u32 s12, s18, 0x83c00
	s_addc_u32 s13, s19, 0
	s_add_u32 s16, s18, 0x2f00000
	s_addc_u32 s17, s19, 0
	s_cmp_gt_i32 s2, 21
	s_cselect_b64 s[0:1], -1, 0
	v_writelane_b32 v250, s0, 4
	s_cmp_lt_i32 s2, 22
	v_readfirstlane_b32 s10, v8
	v_writelane_b32 v250, s1, 5
	s_cbranch_scc1 .LBB0_91
	s_add_u32 s4, s2, 0xffffffea
	s_addc_u32 s5, 0, -1
	v_mov_b64_e32 v[0:1], 0x580
	v_cmp_lt_u64_e32 vcc, s[4:5], v[0:1]
	s_cbranch_vccz .LBB0_92
	s_and_b32 s0, s4, 7
	s_lshr_b32 s1, s4, 3
	s_mulk_i32 s0, 0xb0
	s_add_i32 s0, s0, s1
	s_and_b32 s1, s0, 0xffff
	s_mul_i32 s1, s1, 0xba2f
	s_lshr_b32 s1, s1, 22
	s_lshl_b32 s3, s1, 2
	s_mulk_i32 s1, 0x58
	s_sub_i32 s0, s0, s1
	s_and_b32 s1, s0, 3
	s_or_b32 s1, s1, s3
	s_and_b32 s3, s1, 0xfff
	s_bfe_u32 s56, s0, 0xe0002
	s_cbranch_execnz .LBB0_93
	s_branch .LBB0_124
